# prologue adaLN GEMV: 16 weight-row loads in flight per wave instead of 4 with an immediate wait (same accumulation order); on top of DPP scans
# speedup vs baseline: 1.0010x; 1.0010x over previous
; __device__ __forceinline__ void prologue(CParams& p, float* smf) {
;     ...
;         for (int wi = blockIdx.x; wi < 4 * 96; wi += gridDim.x) {
;             const int layer = wi / 96, cb = wi - layer * 96;
;             const float* w = p.ada_w + (size_t)layer * 1024 * 6144 + cb * 64 + cl;
;             float s0 = 0.f, s1 = 0.f, s2 = 0.f;
;             for (int k = kg * 256; k < kg * 256 + 256; ++k) {
;                 const float wv = w[(size_t)k * 6144];
;                 s0 += sc[k] * wv; s1 += sc[1024 + k] * wv; s2 += sc[2048 + k] * wv;
;             }
;             lds_sync();
;             red[(kg * 3 + 0) * 64 + cl] = s0; red[(kg * 3 + 1) * 64 + cl] = s1; red[(kg * 3 + 2) * 64 + cl] = s2;
;             lds_sync();
;             if (tid < 192) {
;                 const int sgi = tid >> 6;
;                 const float v = red[(0 * 3 + sgi) * 64 + cl] + red[(1 * 3 + sgi) * 64 + cl] + red[(2 * 3 + sgi) * 64 + cl] + red[(3 * 3 + sgi) * 64 + cl];
;                 const int n = cb * 64 + cl;
;                 mod[((size_t)layer * 3 + sgi) * 6144 + n] = v + p.ada_b[layer * 6144 + n];
;             }
;         }
.LBB0_56:
	s_mov_b64 s[42:43], 0x6000
	v_lshl_add_u64 v[72:73], v[4:5], 0, s[6:7]
	global_load_dword v40, v[72:73], off
	v_lshl_add_u64 v[72:73], v[72:73], 0, s[42:43]
	global_load_dword v42, v[72:73], off
	v_lshl_add_u64 v[72:73], v[72:73], 0, s[42:43]
	global_load_dword v44, v[72:73], off
	v_lshl_add_u64 v[72:73], v[72:73], 0, s[42:43]
	global_load_dword v46, v[72:73], off
	v_lshl_add_u64 v[72:73], v[72:73], 0, s[42:43]
	global_load_dword v48, v[72:73], off
	v_lshl_add_u64 v[72:73], v[72:73], 0, s[42:43]
	global_load_dword v50, v[72:73], off
	v_lshl_add_u64 v[72:73], v[72:73], 0, s[42:43]
	global_load_dword v52, v[72:73], off
	v_lshl_add_u64 v[72:73], v[72:73], 0, s[42:43]
	global_load_dword v54, v[72:73], off
	v_lshl_add_u64 v[72:73], v[72:73], 0, s[42:43]
	global_load_dword v56, v[72:73], off
	v_lshl_add_u64 v[72:73], v[72:73], 0, s[42:43]
	global_load_dword v58, v[72:73], off
	v_lshl_add_u64 v[72:73], v[72:73], 0, s[42:43]
	global_load_dword v60, v[72:73], off
	v_lshl_add_u64 v[72:73], v[72:73], 0, s[42:43]
	global_load_dword v62, v[72:73], off
	v_lshl_add_u64 v[72:73], v[72:73], 0, s[42:43]
	global_load_dword v64, v[72:73], off
	v_lshl_add_u64 v[72:73], v[72:73], 0, s[42:43]
	global_load_dword v66, v[72:73], off
	v_lshl_add_u64 v[72:73], v[72:73], 0, s[42:43]
	global_load_dword v68, v[72:73], off
	v_lshl_add_u64 v[72:73], v[72:73], 0, s[42:43]
	global_load_dword v70, v[72:73], off
	s_add_u32 s6, s6, 0x60000
	s_addc_u32 s7, s7, 0
	ds_read_b128 v[20:23], v14
	ds_read_b128 v[24:27], v14 offset:4096
	ds_read_b128 v[28:31], v14 offset:8192
	s_waitcnt lgkmcnt(0)
	v_mov_b32_e32 v39, v24
	v_mov_b32_e32 v38, v28
	v_mov_b32_e32 v24, v29
	v_mov_b32_e32 v28, v30
	v_mov_b32_e32 v29, v26
	v_mov_b32_e32 v26, v31
	s_waitcnt vmcnt(15)
	v_fmac_f32_e32 v13, v40, v20
	v_pk_fma_f32 v[6:7], v[40:41], v[38:39], v[6:7] op_sel_hi:[0,1,1]
	s_waitcnt vmcnt(14)
	v_fmac_f32_e32 v13, v42, v21
	v_pk_fma_f32 v[6:7], v[42:43], v[24:25], v[6:7] op_sel_hi:[0,1,1]
	s_waitcnt vmcnt(13)
	v_fmac_f32_e32 v13, v44, v22
	v_pk_fma_f32 v[6:7], v[44:45], v[28:29], v[6:7] op_sel_hi:[0,1,1]
	s_waitcnt vmcnt(12)
	v_fmac_f32_e32 v13, v46, v23
	v_pk_fma_f32 v[6:7], v[46:47], v[26:27], v[6:7] op_sel_hi:[0,1,1]
	ds_read_b128 v[20:23], v14 offset:16
	ds_read_b128 v[24:27], v14 offset:4112
	ds_read_b128 v[28:31], v14 offset:8208
	s_waitcnt lgkmcnt(0)
	v_mov_b32_e32 v39, v24
	v_mov_b32_e32 v38, v28
	v_mov_b32_e32 v24, v29
	v_mov_b32_e32 v28, v30
	v_mov_b32_e32 v29, v26
	v_mov_b32_e32 v26, v31
	s_waitcnt vmcnt(11)
	v_fmac_f32_e32 v13, v48, v20
	v_pk_fma_f32 v[6:7], v[48:49], v[38:39], v[6:7] op_sel_hi:[0,1,1]
	s_waitcnt vmcnt(10)
	v_fmac_f32_e32 v13, v50, v21
	v_pk_fma_f32 v[6:7], v[50:51], v[24:25], v[6:7] op_sel_hi:[0,1,1]
	s_waitcnt vmcnt(9)
	v_fmac_f32_e32 v13, v52, v22
	v_pk_fma_f32 v[6:7], v[52:53], v[28:29], v[6:7] op_sel_hi:[0,1,1]
	s_waitcnt vmcnt(8)
	v_fmac_f32_e32 v13, v54, v23
	v_pk_fma_f32 v[6:7], v[54:55], v[26:27], v[6:7] op_sel_hi:[0,1,1]
	ds_read_b128 v[20:23], v14 offset:32
	ds_read_b128 v[24:27], v14 offset:4128
	ds_read_b128 v[28:31], v14 offset:8224
	s_waitcnt lgkmcnt(0)
	v_mov_b32_e32 v39, v24
	v_mov_b32_e32 v38, v28
	v_mov_b32_e32 v24, v29
	v_mov_b32_e32 v28, v30
	v_mov_b32_e32 v29, v26
	v_mov_b32_e32 v26, v31
	s_waitcnt vmcnt(7)
	v_fmac_f32_e32 v13, v56, v20
	v_pk_fma_f32 v[6:7], v[56:57], v[38:39], v[6:7] op_sel_hi:[0,1,1]
	s_waitcnt vmcnt(6)
	v_fmac_f32_e32 v13, v58, v21
	v_pk_fma_f32 v[6:7], v[58:59], v[24:25], v[6:7] op_sel_hi:[0,1,1]
	s_waitcnt vmcnt(5)
	v_fmac_f32_e32 v13, v60, v22
	v_pk_fma_f32 v[6:7], v[60:61], v[28:29], v[6:7] op_sel_hi:[0,1,1]
	s_waitcnt vmcnt(4)
	v_fmac_f32_e32 v13, v62, v23
	v_pk_fma_f32 v[6:7], v[62:63], v[26:27], v[6:7] op_sel_hi:[0,1,1]
	ds_read_b128 v[20:23], v14 offset:48
	ds_read_b128 v[24:27], v14 offset:4144
	ds_read_b128 v[28:31], v14 offset:8240
	s_waitcnt lgkmcnt(0)
	v_mov_b32_e32 v39, v24
	v_mov_b32_e32 v38, v28
	v_mov_b32_e32 v24, v29
	v_mov_b32_e32 v28, v30
	v_mov_b32_e32 v29, v26
	v_mov_b32_e32 v26, v31
	s_waitcnt vmcnt(3)
	v_fmac_f32_e32 v13, v64, v20
	v_pk_fma_f32 v[6:7], v[64:65], v[38:39], v[6:7] op_sel_hi:[0,1,1]
	s_waitcnt vmcnt(2)
	v_fmac_f32_e32 v13, v66, v21
	v_pk_fma_f32 v[6:7], v[66:67], v[24:25], v[6:7] op_sel_hi:[0,1,1]
	s_waitcnt vmcnt(1)
	v_fmac_f32_e32 v13, v68, v22
	v_pk_fma_f32 v[6:7], v[68:69], v[28:29], v[6:7] op_sel_hi:[0,1,1]
	s_waitcnt vmcnt(0)
	v_fmac_f32_e32 v13, v70, v23
	v_pk_fma_f32 v[6:7], v[70:71], v[26:27], v[6:7] op_sel_hi:[0,1,1]
	v_add_u32_e32 v14, 64, v14
	s_cmp_eq_u32 s6, 0x600000
	s_cbranch_scc0 .LBB0_56
	s_barrier
	ds_write_b32 v9, v13 offset:12288
	ds_write2st64_b32 v10, v7, v6 offset0:49 offset1:50
	s_waitcnt lgkmcnt(0)
	s_barrier
	s_and_saveexec_b64 s[6:7], vcc
	s_cbranch_execz .LBB0_54
	s_mul_i32 s14, s12, 0xffffffa0
	s_add_i32 s14, s14, s9
	v_lshl_or_b32 v4, s14, 6, v18
	v_add_u32_e32 v6, s13, v4
	v_ashrrev_i32_e32 v7, 31, v6
	v_lshl_add_u64 v[6:7], v[6:7], 2, s[46:47]
	global_load_dword v13, v[6:7], off
	ds_read_b32 v19, v8 offset:12288
	ds_read2st64_b32 v[6:7], v11 offset0:51 offset1:54
	ds_read_b32 v20, v11 offset:14592
	v_mad_i64_i32 v[14:15], s[12:13], s12, 3, v[0:1]
	v_mov_b64_e32 v[16:17], s[4:5]
	s_waitcnt lgkmcnt(1)
	v_add_f32_e32 v6, v19, v6
	v_mad_u64_u32 v[16:17], s[12:13], v14, s84, v[16:17]
	v_add_f32_e32 v6, v6, v7
	v_mad_i32_i24 v17, v15, s84, v17
	v_ashrrev_i32_e32 v5, 31, v4
	s_waitcnt lgkmcnt(0)
	v_add_f32_e32 v6, v6, v20
	v_lshl_add_u64 v[4:5], v[4:5], 2, v[16:17]
	s_waitcnt vmcnt(0)
	v_add_f32_e32 v6, v6, v13
	global_store_dword v[4:5], v6, off
	s_branch .LBB0_54
